# grid barrier: cross-XCD counter polled directly by each XCD's last arriver (no returned ticket, no second generation word)
# baseline (speedup 1.0000x reference)
; DI unsigned xb_ld(unsigned* q) { return __hip_atomic_load(q, __ATOMIC_RELAXED, __HIP_MEMORY_SCOPE_AGENT); }
; DI unsigned xb_add(unsigned* q, unsigned v) { return __hip_atomic_fetch_add(q, v, __ATOMIC_RELAXED, __HIP_MEMORY_SCOPE_AGENT); }
; #define XB_SPIN(cond, bar) do { unsigned _sp = 0; while (cond) { __builtin_amdgcn_s_sleep(1); \
;     if ((++_sp & 255u) == 0u) { if (xb_ld(&(bar)[XB_TMO])) break; if (_sp > XB_SPIN_CAP) { atomicAdd(&(bar)[XB_TMO], 1u); break; } } } } while (0)
; DI void grid_bar(unsigned* bar, volatile LAS unsigned* st, int wid) {
;     ...
;             const unsigned old = xb_add(&bar[XB_XSUB(x)], 1u);
;             const unsigned gen = old / nloc;
;             if (old + 1u == (gen + 1u) * nloc) {
;                 __builtin_amdgcn_fence(__ATOMIC_RELEASE, "agent");
;                 asm volatile("s_waitcnt vmcnt(0)" ::: "memory");
;                 const unsigned og = xb_add(&bar[XB_TOP], 1u);
;                 const unsigned tg = og / nx;
;                 if (og + 1u == (tg + 1u) * nx) xb_add(&bar[XB_TOPGEN], 1u);
;                 else XB_SPIN(xb_ld(&bar[XB_TOPGEN]) == tg, bar);
;                 __builtin_amdgcn_fence(__ATOMIC_ACQUIRE, "agent");
;                 xb_add(&bar[XB_XGEN(x)], 1u);
;                 asm volatile("s_waitcnt vmcnt(0)" ::: "memory");
.LBB0_275:
	s_andn2_saveexec_b64 s[12:13], s[12:13]
	s_cbranch_execz .LBB0_295
	buffer_wbl2 sc1
	s_waitcnt vmcnt(0) lgkmcnt(0)
	v_add_u32_e32 v4, 1, v1
	v_mul_lo_u32 v4, v4, v0
	v_mov_b32_e32 v2, 0xcd83000
	v_mov_b32_e32 v3, 1
	global_atomic_add v2, v3, s[8:9] offset:1024
	s_mov_b32 s28, 0
.Lxb2_0_spin:
	global_load_dword v5, v2, s[8:9] offset:1024 sc1
	s_waitcnt vmcnt(0)
	v_cmp_ge_u32_e32 vcc, v5, v4
	s_cbranch_vccnz .Lxb2_0_done
	s_sleep 1
	s_add_i32 s28, s28, 1
	s_cmp_lt_u32 s28, 0x4000
	s_cbranch_scc1 .Lxb2_0_spin
.Lxb2_0_done:
	s_mov_b64 s[8:9], exec
	v_mbcnt_lo_u32_b32 v0, s8, 0
	v_mbcnt_hi_u32_b32 v0, s9, v0
	v_cmp_eq_u32_e32 vcc, 0, v0
	s_waitcnt vmcnt(0)
	buffer_inv sc1
	s_and_saveexec_b64 s[12:13], vcc
	s_cbranch_execz .LBB0_294
	s_bcnt1_i32_b64 s8, s[8:9]
	v_mov_b32_e32 v0, 0x2000
	v_mov_b32_e32 v1, s8
	global_atomic_add v0, v1, s[10:11] offset:1024
